# group barrier on a single XCC: flag-array barrier (each workgroup stores its step number to its own word, 32 lanes poll the 32 words) instead of ticket atomic + leader release
# speedup vs baseline: 1.0108x; 1.0108x over previous
.LBB0_524:
	s_waitcnt lgkmcnt(0)
	v_cmp_eq_u32_e32 vcc, 1, v0
	v_cmp_eq_u32_e64 s[22:23], s68, v3
	s_and_b64 vcc, vcc, s[22:23]
	s_cbranch_vccz .Lxb_slow
	s_add_i32 s8, s80, 1
	s_lshl_b32 s9, s33, 2
	s_add_u32 s22, s4, 0x3800
	s_addc_u32 s23, s5, 0
	s_add_u32 s20, s22, s9
	s_addc_u32 s21, s23, 0
	v_mov_b32_e32 v4, s8
	global_store_dword v2, v4, s[20:21]
	s_mov_b32 exec_lo, -1
	s_mov_b32 exec_hi, 0
	v_mbcnt_lo_u32_b32 v5, -1, 0
	v_lshlrev_b32_e32 v5, 2, v5
.Lxb_poll:
	global_load_dword v6, v5, s[22:23] sc1
	s_waitcnt vmcnt(0)
	v_cmp_gt_u32_e32 vcc, s8, v6
	s_cbranch_vccz .Lxb_acq
	s_sleep 1
	s_branch .Lxb_poll
.Lxb_acq:
	buffer_inv sc1
	s_waitcnt vmcnt(0)
	s_branch .LBB0_221
